# attention wait fix + L0 out-proj wait removal + first-k-iteration vmcnt(N) in 14 GEMM loops
# speedup vs baseline: 1.0026x; 1.0011x over previous
; DEV int tid_l() { int t = threadIdx.x; asm volatile("" : "+v"(t)); return t; }
; DEV int stage_next(int s) { return (s == 2 * GS_STAGE) ? 0 : s + GS_STAGE; }
; template <int WAIT0>
; DEV void gk_main(f32x16 (&acc)[2][2], const GTile& t, int s0) {
;   const int tid = tid_l(), lane = tid & 63, wid = __builtin_amdgcn_readfirstlane(tid >> 6), wm = wid & 1, wn = wid >> 1, l32 = lane & 31, hi = lane >> 5;
;   GK_SRC(t)
;   const int sw = (l32 >> 1) & 7;
;   int xk[4], wk[4];
; #pragma unroll
;   for (int ks = 0; ks < 4; ++ks) { const int ko = ((2 * ks + hi) ^ sw) << 4; xk[ks] = GS_A + (64 * wm + l32) * 128 + ko; wk[ks] = GS_B + (64 * wn + l32) * 128 + ko; }
;   const int nk = t.K >> 6;
;     ...
;   vm_wait_bar<WAIT0>();
;   int stc = s0, std_ = stage_next(stage_next(s0));
.LBB0_273:
	s_cmp_lg_u32 s2, 0
	s_cbranch_scc0 .LBB0_284
	s_bitcmp0_b32 s2, 0
	s_mov_b64 s[6:7], -1
	s_cbranch_scc1 .LBB0_278
	v_mov_b32_e32 v1, v176
	s_waitcnt vmcnt(22) lgkmcnt(0)
	s_barrier
	v_readfirstlane_b32 s3, v1
	s_ashr_i32 s6, s3, 6
	v_bfe_u32 v0, v1, 3, 3
	v_and_b32_e32 v2, 31, v1
	v_lshl_or_b32 v0, s6, 3, v0
	v_lshrrev_b32_e32 v3, 1, v0
	v_and_or_b32 v6, s3, 64, v2
	s_lshr_b32 s3, s3, 1
	v_xor_b32_e32 v3, v3, v1
	s_and_b32 s3, s3, 0x1ffffc0
	v_lshlrev_b32_e32 v3, 4, v3
	v_or_b32_e32 v2, s3, v2
	s_lshl_b32 s3, s6, 10
	v_and_b32_e32 v4, 0x70, v3
	v_bfe_u32 v3, v1, 5, 1
	v_lshrrev_b32_e32 v5, 1, v1
	v_bfe_u32 v1, v1, 1, 3
	s_add_i32 s10, s3, 0
	s_add_i32 s3, s9, 0xc000
	v_bitop3_b32 v5, v3, v5, 7 bitop3:0x78
	v_bitop3_b32 v7, v3, v1, 2 bitop3:0x36
	v_bitop3_b32 v8, v3, v1, 4 bitop3:0x36
	v_bitop3_b32 v1, v3, v1, 6 bitop3:0x36
	s_cmp_lg_u32 s9, 0x18000
	v_lshlrev_b32_e32 v2, 7, v2
	v_lshlrev_b32_e32 v5, 4, v5
	v_lshlrev_b32_e32 v7, 4, v7
	v_lshlrev_b32_e32 v8, 4, v8
	v_lshlrev_b32_e32 v1, 4, v1
	s_cselect_b32 s8, s3, 0
	s_add_i32 s3, s8, 0xc000
	v_or_b32_e32 v83, v2, v5
	v_or_b32_e32 v81, v2, v7
	v_or_b32_e32 v79, v2, v8
	v_or_b32_e32 v77, v2, v1
	v_add_u32_e32 v2, 0xc0, v0
	s_cmp_lg_u32 s8, 0x18000
	v_ashrrev_i32_e32 v3, 31, v2
	s_cselect_b32 s11, s3, 0
	s_add_u32 s6, s4, 0x100
	v_lshlrev_b64 v[2:3], 11, v[2:3]
	s_addc_u32 s7, s5, 0
	v_or_b32_e32 v2, v2, v4
	v_lshl_add_u64 v[64:65], s[6:7], 0, v[2:3]
	v_add_u32_e32 v2, 0x80, v0
	v_ashrrev_i32_e32 v3, 31, v2
	v_lshlrev_b64 v[2:3], 11, v[2:3]
	v_or_b32_e32 v2, v2, v4
	v_lshlrev_b32_e32 v6, 7, v6
	v_lshl_add_u64 v[66:67], s[6:7], 0, v[2:3]
	v_add_u32_e32 v2, 64, v0
	v_or_b32_e32 v76, v1, v6
	v_ashrrev_i32_e32 v3, 31, v2
	v_ashrrev_i32_e32 v1, 31, v0
	v_lshlrev_b64 v[2:3], 11, v[2:3]
	v_lshlrev_b64 v[0:1], 11, v[0:1]
	v_or_b32_e32 v2, v2, v4
	v_or_b32_e32 v0, v0, v4
	v_lshl_add_u64 v[68:69], s[6:7], 0, v[2:3]
	v_lshl_add_u64 v[70:71], s[6:7], 0, v[0:1]
	v_readlane_b32 s6, v231, 15
	v_readlane_b32 s7, v231, 16
	v_or_b32_e32 v82, v5, v6
	v_or_b32_e32 v80, v7, v6
	v_lshl_add_u64 v[74:75], s[6:7], 0, v[0:1]
	v_mov_b32_e32 v0, 0
	v_or_b32_e32 v78, v8, v6
	v_lshl_add_u64 v[72:73], s[6:7], 0, v[2:3]
	s_mov_b64 s[6:7], 0
	s_mov_b32 s3, s9
	v_mov_b32_e32 v1, v0
	v_mov_b32_e32 v2, v0
	v_mov_b32_e32 v3, v0
	v_mov_b32_e32 v4, v0
	v_mov_b32_e32 v5, v0
	v_mov_b32_e32 v6, v0
	v_mov_b32_e32 v7, v0
	v_mov_b32_e32 v8, v0
	v_mov_b32_e32 v9, v0
	v_mov_b32_e32 v10, v0
	v_mov_b32_e32 v11, v0
	v_mov_b32_e32 v12, v0
	v_mov_b32_e32 v13, v0
	v_mov_b32_e32 v14, v0
	v_mov_b32_e32 v15, v0
	v_mov_b32_e32 v32, v0
	v_mov_b32_e32 v33, v0
	v_mov_b32_e32 v34, v0
	v_mov_b32_e32 v35, v0
	v_mov_b32_e32 v36, v0
	v_mov_b32_e32 v37, v0
	v_mov_b32_e32 v38, v0
	v_mov_b32_e32 v39, v0
	v_mov_b32_e32 v40, v0
	v_mov_b32_e32 v41, v0
	v_mov_b32_e32 v42, v0
	v_mov_b32_e32 v43, v0
	v_mov_b32_e32 v44, v0
	v_mov_b32_e32 v45, v0
	v_mov_b32_e32 v46, v0
	v_mov_b32_e32 v47, v0
	v_mov_b32_e32 v16, v0
	v_mov_b32_e32 v17, v0
	v_mov_b32_e32 v18, v0
	v_mov_b32_e32 v19, v0
	v_mov_b32_e32 v20, v0
	v_mov_b32_e32 v21, v0
	v_mov_b32_e32 v22, v0
	v_mov_b32_e32 v23, v0
	v_mov_b32_e32 v24, v0
	v_mov_b32_e32 v25, v0
	v_mov_b32_e32 v26, v0
	v_mov_b32_e32 v27, v0
	v_mov_b32_e32 v28, v0
	v_mov_b32_e32 v29, v0
	v_mov_b32_e32 v30, v0
	v_mov_b32_e32 v31, v0
	v_mov_b32_e32 v48, v0
	v_mov_b32_e32 v49, v0
	v_mov_b32_e32 v50, v0
	v_mov_b32_e32 v51, v0
	v_mov_b32_e32 v52, v0
	v_mov_b32_e32 v53, v0
	v_mov_b32_e32 v54, v0
	v_mov_b32_e32 v55, v0
	v_mov_b32_e32 v56, v0
	v_mov_b32_e32 v57, v0
	v_mov_b32_e32 v58, v0
	v_mov_b32_e32 v59, v0
	v_mov_b32_e32 v60, v0
	v_mov_b32_e32 v61, v0
	v_mov_b32_e32 v62, v0
	v_mov_b32_e32 v63, v0
	s_add_i32 s99, s3, 0
	v_add_u32_e32 v252, s99, v82
	v_add_u32_e32 v253, s99, v83
	ds_read_b128 v[84:87], v252
	ds_read_b128 v[88:91], v252 offset:4096
	ds_read_b128 v[92:95], v253 offset:16384
	ds_read_b128 v[96:99], v253 offset:20480
	s_mov_b64 vcc, -1
	s_branch .Lfws_276

; DEV int tid_l() { int t = threadIdx.x; asm volatile("" : "+v"(t)); return t; }
; DEV int stage_next(int s) { return (s == 2 * GS_STAGE) ? 0 : s + GS_STAGE; }
; template <int WAIT0>
; DEV void gk_main(f32x16 (&acc)[2][2], const GTile& t, int s0) {
;   const int tid = tid_l(), lane = tid & 63, wid = __builtin_amdgcn_readfirstlane(tid >> 6), wm = wid & 1, wn = wid >> 1, l32 = lane & 31, hi = lane >> 5;
;   GK_SRC(t)
;   const int sw = (l32 >> 1) & 7;
;   int xk[4], wk[4];
; #pragma unroll
;   for (int ks = 0; ks < 4; ++ks) { const int ko = ((2 * ks + hi) ^ sw) << 4; xk[ks] = GS_A + (64 * wm + l32) * 128 + ko; wk[ks] = GS_B + (64 * wn + l32) * 128 + ko; }
;   const int nk = t.K >> 6;
;     ...
;   vm_wait_bar<WAIT0>();
;   int stc = s0, std_ = stage_next(stage_next(s0));
.LBB0_278:
	s_and_b64 vcc, exec, s[6:7]
	s_cbranch_vccz .LBB0_282
	s_nop 9
	v_mov_b32_e32 v1, v176
	s_waitcnt vmcnt(22) lgkmcnt(0)
	s_barrier
	v_readfirstlane_b32 s3, v1
	s_ashr_i32 s6, s3, 6
	v_bfe_u32 v0, v1, 3, 3
	v_and_b32_e32 v2, 31, v1
	v_lshl_or_b32 v0, s6, 3, v0
	v_lshrrev_b32_e32 v3, 1, v0
	v_and_or_b32 v6, s3, 64, v2
	s_lshr_b32 s3, s3, 1
	v_xor_b32_e32 v3, v3, v1
	s_and_b32 s3, s3, 0x1ffffc0
	v_lshlrev_b32_e32 v3, 4, v3
	v_or_b32_e32 v2, s3, v2
	s_lshl_b32 s3, s6, 10
	v_and_b32_e32 v4, 0x70, v3
	v_bfe_u32 v3, v1, 5, 1
	v_lshrrev_b32_e32 v5, 1, v1
	v_bfe_u32 v1, v1, 1, 3
	s_add_i32 s10, s3, 0
	s_add_i32 s3, s9, 0xc000
	v_bitop3_b32 v5, v3, v5, 7 bitop3:0x78
	v_bitop3_b32 v7, v3, v1, 2 bitop3:0x36
	v_bitop3_b32 v8, v3, v1, 4 bitop3:0x36
	v_bitop3_b32 v1, v3, v1, 6 bitop3:0x36
	s_cmp_lg_u32 s9, 0x18000
	v_lshlrev_b32_e32 v2, 7, v2
	v_lshlrev_b32_e32 v5, 4, v5
	v_lshlrev_b32_e32 v7, 4, v7
	v_lshlrev_b32_e32 v8, 4, v8
	v_lshlrev_b32_e32 v1, 4, v1
	s_cselect_b32 s8, s3, 0
	s_add_i32 s3, s8, 0xc000
	v_or_b32_e32 v83, v2, v5
	v_or_b32_e32 v81, v2, v7
	v_or_b32_e32 v79, v2, v8
	v_or_b32_e32 v77, v2, v1
	v_add_u32_e32 v2, 0xc0, v0
	s_cmp_lg_u32 s8, 0x18000
	v_ashrrev_i32_e32 v3, 31, v2
	s_cselect_b32 s11, s3, 0
	s_add_u32 s6, s4, 0x100
	v_lshlrev_b64 v[2:3], 11, v[2:3]
	s_addc_u32 s7, s5, 0
	v_or_b32_e32 v2, v2, v4
	v_lshl_add_u64 v[64:65], s[6:7], 0, v[2:3]
	v_add_u32_e32 v2, 0x80, v0
	v_ashrrev_i32_e32 v3, 31, v2
	v_lshlrev_b64 v[2:3], 11, v[2:3]
	v_or_b32_e32 v2, v2, v4
	v_lshlrev_b32_e32 v6, 7, v6
	v_lshl_add_u64 v[66:67], s[6:7], 0, v[2:3]
	v_add_u32_e32 v2, 64, v0
	v_or_b32_e32 v76, v1, v6
	v_ashrrev_i32_e32 v3, 31, v2
	v_ashrrev_i32_e32 v1, 31, v0
	v_lshlrev_b64 v[2:3], 11, v[2:3]
	v_lshlrev_b64 v[0:1], 11, v[0:1]
	v_or_b32_e32 v2, v2, v4
	v_or_b32_e32 v0, v0, v4
	v_lshl_add_u64 v[68:69], s[6:7], 0, v[2:3]
	v_lshl_add_u64 v[70:71], s[6:7], 0, v[0:1]
	v_readlane_b32 s6, v231, 15
	v_readlane_b32 s7, v231, 16
	v_or_b32_e32 v82, v5, v6
	v_or_b32_e32 v80, v7, v6
	v_lshl_add_u64 v[74:75], s[6:7], 0, v[0:1]
	v_mov_b32_e32 v0, 0
	v_or_b32_e32 v78, v8, v6
	v_lshl_add_u64 v[72:73], s[6:7], 0, v[2:3]
	s_mov_b64 s[6:7], 0
	s_mov_b32 s3, s9
	v_mov_b32_e32 v1, v0
	v_mov_b32_e32 v2, v0
	v_mov_b32_e32 v3, v0
	v_mov_b32_e32 v4, v0
	v_mov_b32_e32 v5, v0
	v_mov_b32_e32 v6, v0
	v_mov_b32_e32 v7, v0
	v_mov_b32_e32 v8, v0
	v_mov_b32_e32 v9, v0
	v_mov_b32_e32 v10, v0
	v_mov_b32_e32 v11, v0
	v_mov_b32_e32 v12, v0
	v_mov_b32_e32 v13, v0
	v_mov_b32_e32 v14, v0
	v_mov_b32_e32 v15, v0
	v_mov_b32_e32 v32, v0
	v_mov_b32_e32 v33, v0
	v_mov_b32_e32 v34, v0
	v_mov_b32_e32 v35, v0
	v_mov_b32_e32 v36, v0
	v_mov_b32_e32 v37, v0
	v_mov_b32_e32 v38, v0
	v_mov_b32_e32 v39, v0
	v_mov_b32_e32 v40, v0
	v_mov_b32_e32 v41, v0
	v_mov_b32_e32 v42, v0
	v_mov_b32_e32 v43, v0
	v_mov_b32_e32 v44, v0
	v_mov_b32_e32 v45, v0
	v_mov_b32_e32 v46, v0
	v_mov_b32_e32 v47, v0
	v_mov_b32_e32 v16, v0
	v_mov_b32_e32 v17, v0
	v_mov_b32_e32 v18, v0
	v_mov_b32_e32 v19, v0
	v_mov_b32_e32 v20, v0
	v_mov_b32_e32 v21, v0
	v_mov_b32_e32 v22, v0
	v_mov_b32_e32 v23, v0
	v_mov_b32_e32 v24, v0
	v_mov_b32_e32 v25, v0
	v_mov_b32_e32 v26, v0
	v_mov_b32_e32 v27, v0
	v_mov_b32_e32 v28, v0
	v_mov_b32_e32 v29, v0
	v_mov_b32_e32 v30, v0
	v_mov_b32_e32 v31, v0
	v_mov_b32_e32 v48, v0
	v_mov_b32_e32 v49, v0
	v_mov_b32_e32 v50, v0
	v_mov_b32_e32 v51, v0
	v_mov_b32_e32 v52, v0
	v_mov_b32_e32 v53, v0
	v_mov_b32_e32 v54, v0
	v_mov_b32_e32 v55, v0
	v_mov_b32_e32 v56, v0
	v_mov_b32_e32 v57, v0
	v_mov_b32_e32 v58, v0
	v_mov_b32_e32 v59, v0
	v_mov_b32_e32 v60, v0
	v_mov_b32_e32 v61, v0
	v_mov_b32_e32 v62, v0
	v_mov_b32_e32 v63, v0
	s_add_i32 s99, s3, 0
	v_add_u32_e32 v252, s99, v82
	v_add_u32_e32 v253, s99, v83
	ds_read_b128 v[84:87], v252
	ds_read_b128 v[88:91], v252 offset:4096
	ds_read_b128 v[92:95], v253 offset:16384
	ds_read_b128 v[96:99], v253 offset:20480
	s_mov_b64 vcc, -1
	s_branch .Lfws_280
